# nsa vmcnt fix + EP_U epilogue pointer resolve simplified
# speedup vs baseline: 1.0063x; 1.0063x over previous
.LBB0_678:
	v_add_u32_e32 v140, s87, v159
	ds_read_b128 v[80:83], v140
	ds_read_b128 v[112:115], v140 offset:1024
	ds_read_b128 v[136:139], v140 offset:2048
	ds_read_b128 v[140:143], v140 offset:3072
	s_add_i32 s39, s20, 2
	s_add_u32 s34, s30, 0x80
	s_addc_u32 s21, s31, 0
	s_cmp_eq_u32 s48, s20
	s_cselect_b32 s20, s36, s34
	s_cselect_b32 s21, s37, s21
	s_cselect_b32 s35, s11, s38
	s_cselect_b32 s34, s10, s25
	v_lshl_add_u64 v[156:157], s[30:31], 0, v[154:155]
	s_add_i32 m0, s23, 0xc000
	ds_read_b128 v[170:173], v168
	ds_read_b128 v[174:177], v168 offset:1024
	ds_read_b128 v[178:181], v168 offset:2048
	ds_read_b128 v[182:185], v168 offset:3072
	ds_read_b128 v[186:189], v168 offset:4096
	ds_read_b128 v[190:193], v168 offset:5120
	ds_read_b128 v[194:197], v168 offset:6144
	ds_read_b128 v[198:201], v168 offset:7168
	global_load_lds_dwordx4 v[156:157], off
	v_lshl_add_u64 v[156:157], s[30:31], 0, v[152:153]
	s_add_i32 m0, s23, 0xe000
	s_nop 0
	global_load_lds_dwordx4 v[156:157], off
	s_waitcnt lgkmcnt(8)
	s_barrier
	s_waitcnt lgkmcnt(0)
	s_setprio 1
	s_waitcnt lgkmcnt(0)
	v_mfma_f32_16x16x32_bf16 v[132:135], v[80:83], v[170:173], v[132:135]
	v_mfma_f32_16x16x32_bf16 v[124:127], v[136:139], v[170:173], v[124:127]
	v_mfma_f32_16x16x32_bf16 v[116:119], v[80:83], v[178:181], v[116:119]
	v_mfma_f32_16x16x32_bf16 v[104:107], v[136:139], v[178:181], v[104:107]
	v_mfma_f32_16x16x32_bf16 v[96:99], v[80:83], v[186:189], v[96:99]
	v_mfma_f32_16x16x32_bf16 v[88:91], v[136:139], v[186:189], v[88:91]
	v_mfma_f32_16x16x32_bf16 v[76:79], v[80:83], v[194:197], v[76:79]
	v_mfma_f32_16x16x32_bf16 v[68:71], v[136:139], v[194:197], v[68:71]
	v_mfma_f32_16x16x32_bf16 v[132:135], v[112:115], v[174:177], v[132:135]
	v_mfma_f32_16x16x32_bf16 v[124:127], v[140:143], v[174:177], v[124:127]
	v_mfma_f32_16x16x32_bf16 v[116:119], v[112:115], v[182:185], v[116:119]
	v_mfma_f32_16x16x32_bf16 v[104:107], v[140:143], v[182:185], v[104:107]
	v_mfma_f32_16x16x32_bf16 v[96:99], v[112:115], v[190:193], v[96:99]
	v_mfma_f32_16x16x32_bf16 v[88:91], v[140:143], v[190:193], v[88:91]
	v_mfma_f32_16x16x32_bf16 v[76:79], v[112:115], v[198:201], v[76:79]
	v_mfma_f32_16x16x32_bf16 v[68:71], v[140:143], v[198:201], v[68:71]
	s_setprio 0
	s_barrier
	s_add_i32 s42, 0, 0x14000
	v_add_u32_e32 v156, s42, v159
	s_add_i32 s43, s87, s22
	ds_read_b128 v[232:235], v156
	ds_read_b128 v[236:239], v156 offset:1024
	ds_read_b128 v[240:243], v156 offset:2048
	ds_read_b128 v[244:247], v156 offset:3072
	v_lshl_add_u64 v[156:157], s[34:35], 0, v[160:161]
	s_mov_b32 m0, s43
	v_lshl_add_u64 v[202:203], s[34:35], 0, v[148:149]
	global_load_lds_dwordx4 v[156:157], off
	s_add_i32 m0, s43, 0x2000
	s_nop 0
	global_load_lds_dwordx4 v[202:203], off
	s_barrier
	s_waitcnt lgkmcnt(0)
	s_setprio 1
	s_waitcnt lgkmcnt(0)
	v_mfma_f32_16x16x32_bf16 v[128:131], v[232:235], v[170:173], v[128:131]
	v_mfma_f32_16x16x32_bf16 v[120:123], v[240:243], v[170:173], v[120:123]
	v_mfma_f32_16x16x32_bf16 v[108:111], v[232:235], v[178:181], v[108:111]
	v_mfma_f32_16x16x32_bf16 v[100:103], v[240:243], v[178:181], v[100:103]
	v_mfma_f32_16x16x32_bf16 v[92:95], v[232:235], v[186:189], v[92:95]
	v_mfma_f32_16x16x32_bf16 v[84:87], v[240:243], v[186:189], v[84:87]
	v_mfma_f32_16x16x32_bf16 v[72:75], v[232:235], v[194:197], v[72:75]
	v_mfma_f32_16x16x32_bf16 v[64:67], v[240:243], v[194:197], v[64:67]
	v_mfma_f32_16x16x32_bf16 v[128:131], v[236:239], v[174:177], v[128:131]
	v_mfma_f32_16x16x32_bf16 v[120:123], v[244:247], v[174:177], v[120:123]
	v_mfma_f32_16x16x32_bf16 v[108:111], v[236:239], v[182:185], v[108:111]
	v_mfma_f32_16x16x32_bf16 v[100:103], v[244:247], v[182:185], v[100:103]
	v_mfma_f32_16x16x32_bf16 v[92:95], v[236:239], v[190:193], v[92:95]
	v_mfma_f32_16x16x32_bf16 v[84:87], v[244:247], v[190:193], v[84:87]
	v_mfma_f32_16x16x32_bf16 v[72:75], v[236:239], v[198:201], v[72:75]
	v_mfma_f32_16x16x32_bf16 v[64:67], v[244:247], v[198:201], v[64:67]
	s_setprio 0
	s_mov_b32 m0, s23
	v_lshl_add_u64 v[206:207], s[20:21], 0, v[144:145]
	s_barrier
	ds_read_b128 v[170:173], v168 offset:16384
	ds_read_b128 v[174:177], v168 offset:17408
	ds_read_b128 v[178:181], v168 offset:18432
	ds_read_b128 v[182:185], v168 offset:19456
	ds_read_b128 v[186:189], v168 offset:20480
	ds_read_b128 v[190:193], v168 offset:21504
	ds_read_b128 v[194:197], v168 offset:22528
	ds_read_b128 v[198:201], v168 offset:23552
	global_load_lds_dwordx4 v[206:207], off
	v_lshl_add_u64 v[248:249], s[20:21], 0, v[146:147]
	s_mov_b32 m0, s27
	s_nop 0
	global_load_lds_dwordx4 v[248:249], off
	s_barrier
	s_waitcnt lgkmcnt(0)
	s_setprio 1
	s_waitcnt lgkmcnt(0)
	v_mfma_f32_16x16x32_bf16 v[60:63], v[80:83], v[170:173], v[60:63]
	v_mfma_f32_16x16x32_bf16 v[52:55], v[136:139], v[170:173], v[52:55]
	v_mfma_f32_16x16x32_bf16 v[44:47], v[80:83], v[178:181], v[44:47]
	v_mfma_f32_16x16x32_bf16 v[36:39], v[136:139], v[178:181], v[36:39]
	v_mfma_f32_16x16x32_bf16 v[28:31], v[80:83], v[186:189], v[28:31]
	v_mfma_f32_16x16x32_bf16 v[20:23], v[136:139], v[186:189], v[20:23]
	v_mfma_f32_16x16x32_bf16 v[12:15], v[80:83], v[194:197], v[12:15]
	v_mfma_f32_16x16x32_bf16 v[4:7], v[136:139], v[194:197], v[4:7]
	v_mfma_f32_16x16x32_bf16 v[60:63], v[112:115], v[174:177], v[60:63]
	v_mfma_f32_16x16x32_bf16 v[52:55], v[140:143], v[174:177], v[52:55]
	v_mfma_f32_16x16x32_bf16 v[44:47], v[112:115], v[182:185], v[44:47]
	v_mfma_f32_16x16x32_bf16 v[36:39], v[140:143], v[182:185], v[36:39]
	v_mfma_f32_16x16x32_bf16 v[28:31], v[112:115], v[190:193], v[28:31]
	v_mfma_f32_16x16x32_bf16 v[20:23], v[140:143], v[190:193], v[20:23]
	v_mfma_f32_16x16x32_bf16 v[12:15], v[112:115], v[198:201], v[12:15]
	v_mfma_f32_16x16x32_bf16 v[4:7], v[140:143], v[198:201], v[4:7]
	s_setprio 0
	s_barrier
	s_add_u32 s34, s34, s64
	s_addc_u32 s35, s35, s65
	s_add_i32 s42, s42, s22
	v_lshl_add_u64 v[250:251], s[34:35], 0, v[160:161]
	s_mov_b32 m0, s42
	v_lshl_add_u64 v[210:211], s[34:35], 0, v[148:149]
	global_load_lds_dwordx4 v[250:251], off
	s_add_i32 m0, s42, 0x2000
	s_nop 0
	global_load_lds_dwordx4 v[210:211], off
	s_waitcnt vmcnt(6)
	s_barrier
	s_setprio 1
	v_mfma_f32_16x16x32_bf16 v[56:59], v[232:235], v[170:173], v[56:59]
	v_mfma_f32_16x16x32_bf16 v[48:51], v[240:243], v[170:173], v[48:51]
	v_mfma_f32_16x16x32_bf16 v[40:43], v[232:235], v[178:181], v[40:43]
	v_mfma_f32_16x16x32_bf16 v[32:35], v[240:243], v[178:181], v[32:35]
	v_mfma_f32_16x16x32_bf16 v[24:27], v[232:235], v[186:189], v[24:27]
	v_mfma_f32_16x16x32_bf16 v[16:19], v[240:243], v[186:189], v[16:19]
	v_mfma_f32_16x16x32_bf16 v[8:11], v[232:235], v[194:197], v[8:11]
	v_mfma_f32_16x16x32_bf16 v[0:3], v[240:243], v[194:197], v[0:3]
	v_mfma_f32_16x16x32_bf16 v[56:59], v[236:239], v[174:177], v[56:59]
	v_mfma_f32_16x16x32_bf16 v[48:51], v[244:247], v[174:177], v[48:51]
	v_mfma_f32_16x16x32_bf16 v[40:43], v[236:239], v[182:185], v[40:43]
	v_mfma_f32_16x16x32_bf16 v[32:35], v[244:247], v[182:185], v[32:35]
	v_mfma_f32_16x16x32_bf16 v[24:27], v[236:239], v[190:193], v[24:27]
	v_mfma_f32_16x16x32_bf16 v[16:19], v[244:247], v[190:193], v[16:19]
	v_mfma_f32_16x16x32_bf16 v[8:11], v[236:239], v[198:201], v[8:11]
	v_mfma_f32_16x16x32_bf16 v[0:3], v[244:247], v[198:201], v[0:3]
	s_setprio 0
	s_add_i32 s34, 0, 0x18000
	v_add_u32_e32 v140, s34, v159
	s_barrier
	ds_read_b128 v[80:83], v140
	ds_read_b128 v[112:115], v140 offset:1024
	ds_read_b128 v[136:139], v140 offset:2048
	ds_read_b128 v[140:143], v140 offset:3072
	s_add_u32 s20, s20, s64
	s_addc_u32 s21, s21, s65
	s_mov_b32 m0, s28
	v_lshl_add_u64 v[232:233], s[20:21], 0, v[144:145]
	ds_read_b128 v[170:173], v168 offset:32768
	ds_read_b128 v[174:177], v168 offset:33792
	ds_read_b128 v[178:181], v168 offset:34816
	ds_read_b128 v[182:185], v168 offset:35840
	ds_read_b128 v[186:189], v168 offset:36864
	ds_read_b128 v[190:193], v168 offset:37888
	ds_read_b128 v[194:197], v168 offset:38912
	ds_read_b128 v[198:201], v168 offset:39936
	global_load_lds_dwordx4 v[232:233], off
	v_lshl_add_u64 v[232:233], s[20:21], 0, v[146:147]
	s_mov_b32 m0, s29
	s_nop 0
	global_load_lds_dwordx4 v[232:233], off
	s_waitcnt lgkmcnt(8)
	s_barrier
	s_waitcnt lgkmcnt(0)
	s_setprio 1
	s_waitcnt lgkmcnt(0)
	v_mfma_f32_16x16x32_bf16 v[132:135], v[80:83], v[170:173], v[132:135]
	v_mfma_f32_16x16x32_bf16 v[124:127], v[136:139], v[170:173], v[124:127]
	v_mfma_f32_16x16x32_bf16 v[116:119], v[80:83], v[178:181], v[116:119]
	v_mfma_f32_16x16x32_bf16 v[104:107], v[136:139], v[178:181], v[104:107]
	v_mfma_f32_16x16x32_bf16 v[96:99], v[80:83], v[186:189], v[96:99]
	v_mfma_f32_16x16x32_bf16 v[88:91], v[136:139], v[186:189], v[88:91]
	v_mfma_f32_16x16x32_bf16 v[76:79], v[80:83], v[194:197], v[76:79]
	v_mfma_f32_16x16x32_bf16 v[68:71], v[136:139], v[194:197], v[68:71]
	v_mfma_f32_16x16x32_bf16 v[132:135], v[112:115], v[174:177], v[132:135]
	v_mfma_f32_16x16x32_bf16 v[124:127], v[140:143], v[174:177], v[124:127]
	v_mfma_f32_16x16x32_bf16 v[116:119], v[112:115], v[182:185], v[116:119]
	v_mfma_f32_16x16x32_bf16 v[104:107], v[140:143], v[182:185], v[104:107]
	v_mfma_f32_16x16x32_bf16 v[96:99], v[112:115], v[190:193], v[96:99]
	v_mfma_f32_16x16x32_bf16 v[88:91], v[140:143], v[190:193], v[88:91]
	v_mfma_f32_16x16x32_bf16 v[76:79], v[112:115], v[198:201], v[76:79]
	v_mfma_f32_16x16x32_bf16 v[68:71], v[140:143], v[198:201], v[68:71]
	s_setprio 0
	s_barrier
	s_add_i32 s20, 0, 0x1c000
	s_add_i32 s21, s34, s22
	v_add_u32_e32 v169, s20, v159
	v_lshl_add_u64 v[156:157], v[156:157], 0, s[96:97]
	s_mov_b32 m0, s21
	ds_read_b128 v[232:235], v169
	ds_read_b128 v[236:239], v169 offset:1024
	ds_read_b128 v[240:243], v169 offset:2048
	ds_read_b128 v[244:247], v169 offset:3072
	global_load_lds_dwordx4 v[156:157], off
	v_lshl_add_u64 v[156:157], v[202:203], 0, s[96:97]
	s_add_i32 m0, s21, 0x2000
	s_nop 0
	global_load_lds_dwordx4 v[156:157], off
	s_barrier
	s_waitcnt lgkmcnt(0)
	s_setprio 1
	s_waitcnt lgkmcnt(0)
	v_mfma_f32_16x16x32_bf16 v[128:131], v[232:235], v[170:173], v[128:131]
	v_mfma_f32_16x16x32_bf16 v[120:123], v[240:243], v[170:173], v[120:123]
	v_mfma_f32_16x16x32_bf16 v[108:111], v[232:235], v[178:181], v[108:111]
	v_mfma_f32_16x16x32_bf16 v[100:103], v[240:243], v[178:181], v[100:103]
	v_mfma_f32_16x16x32_bf16 v[92:95], v[232:235], v[186:189], v[92:95]
	v_mfma_f32_16x16x32_bf16 v[84:87], v[240:243], v[186:189], v[84:87]
	v_mfma_f32_16x16x32_bf16 v[72:75], v[232:235], v[194:197], v[72:75]
	v_mfma_f32_16x16x32_bf16 v[64:67], v[240:243], v[194:197], v[64:67]
	v_mfma_f32_16x16x32_bf16 v[128:131], v[236:239], v[174:177], v[128:131]
	v_mfma_f32_16x16x32_bf16 v[120:123], v[244:247], v[174:177], v[120:123]
	v_mfma_f32_16x16x32_bf16 v[108:111], v[236:239], v[182:185], v[108:111]
	v_mfma_f32_16x16x32_bf16 v[100:103], v[244:247], v[182:185], v[100:103]
	v_mfma_f32_16x16x32_bf16 v[92:95], v[236:239], v[190:193], v[92:95]
	v_mfma_f32_16x16x32_bf16 v[84:87], v[244:247], v[190:193], v[84:87]
	v_mfma_f32_16x16x32_bf16 v[72:75], v[236:239], v[198:201], v[72:75]
	v_mfma_f32_16x16x32_bf16 v[64:67], v[244:247], v[198:201], v[64:67]
	s_setprio 0
	s_mov_b32 m0, s44
	v_lshl_add_u64 v[156:157], v[206:207], 0, s[96:97]
	s_barrier
	ds_read_b128 v[170:173], v168 offset:49152
	ds_read_b128 v[174:177], v168 offset:50176
	ds_read_b128 v[178:181], v168 offset:51200
	ds_read_b128 v[182:185], v168 offset:52224
	ds_read_b128 v[186:189], v168 offset:53248
	ds_read_b128 v[190:193], v168 offset:54272
	ds_read_b128 v[194:197], v168 offset:55296
	ds_read_b128 v[198:201], v168 offset:56320
	global_load_lds_dwordx4 v[156:157], off
	v_lshl_add_u64 v[156:157], v[248:249], 0, s[96:97]
	s_mov_b32 m0, s45
	s_nop 0
	global_load_lds_dwordx4 v[156:157], off
	s_barrier
	s_waitcnt lgkmcnt(0)
	s_setprio 1
	s_waitcnt lgkmcnt(0)
	v_mfma_f32_16x16x32_bf16 v[60:63], v[80:83], v[170:173], v[60:63]
	v_mfma_f32_16x16x32_bf16 v[52:55], v[136:139], v[170:173], v[52:55]
	v_mfma_f32_16x16x32_bf16 v[44:47], v[80:83], v[178:181], v[44:47]
	v_mfma_f32_16x16x32_bf16 v[36:39], v[136:139], v[178:181], v[36:39]
	v_mfma_f32_16x16x32_bf16 v[28:31], v[80:83], v[186:189], v[28:31]
	v_mfma_f32_16x16x32_bf16 v[20:23], v[136:139], v[186:189], v[20:23]
	v_mfma_f32_16x16x32_bf16 v[12:15], v[80:83], v[194:197], v[12:15]
	v_mfma_f32_16x16x32_bf16 v[4:7], v[136:139], v[194:197], v[4:7]
	v_mfma_f32_16x16x32_bf16 v[60:63], v[112:115], v[174:177], v[60:63]
	v_mfma_f32_16x16x32_bf16 v[52:55], v[140:143], v[174:177], v[52:55]
	v_mfma_f32_16x16x32_bf16 v[44:47], v[112:115], v[182:185], v[44:47]
	v_mfma_f32_16x16x32_bf16 v[36:39], v[140:143], v[182:185], v[36:39]
	v_mfma_f32_16x16x32_bf16 v[28:31], v[112:115], v[190:193], v[28:31]
	v_mfma_f32_16x16x32_bf16 v[20:23], v[140:143], v[190:193], v[20:23]
	v_mfma_f32_16x16x32_bf16 v[12:15], v[112:115], v[198:201], v[12:15]
	v_mfma_f32_16x16x32_bf16 v[4:7], v[140:143], v[198:201], v[4:7]
	s_setprio 0
	s_barrier
	s_add_i32 s20, s20, s22
	v_lshl_add_u64 v[80:81], v[250:251], 0, s[96:97]
	s_mov_b32 m0, s20
	s_nop 0
	global_load_lds_dwordx4 v[80:81], off
	v_lshl_add_u64 v[80:81], v[210:211], 0, s[96:97]
	s_add_i32 m0, s20, 0x2000
	s_nop 0
	global_load_lds_dwordx4 v[80:81], off
	s_waitcnt vmcnt(6)
	s_barrier
	s_setprio 1
	v_mfma_f32_16x16x32_bf16 v[56:59], v[232:235], v[170:173], v[56:59]
	v_mfma_f32_16x16x32_bf16 v[48:51], v[240:243], v[170:173], v[48:51]
	v_mfma_f32_16x16x32_bf16 v[40:43], v[232:235], v[178:181], v[40:43]
	v_mfma_f32_16x16x32_bf16 v[32:35], v[240:243], v[178:181], v[32:35]
	v_mfma_f32_16x16x32_bf16 v[24:27], v[232:235], v[186:189], v[24:27]
	v_mfma_f32_16x16x32_bf16 v[16:19], v[240:243], v[186:189], v[16:19]
	v_mfma_f32_16x16x32_bf16 v[8:11], v[232:235], v[194:197], v[8:11]
	v_mfma_f32_16x16x32_bf16 v[0:3], v[240:243], v[194:197], v[0:3]
	v_mfma_f32_16x16x32_bf16 v[56:59], v[236:239], v[174:177], v[56:59]
	v_mfma_f32_16x16x32_bf16 v[48:51], v[244:247], v[174:177], v[48:51]
	v_mfma_f32_16x16x32_bf16 v[40:43], v[236:239], v[182:185], v[40:43]
	v_mfma_f32_16x16x32_bf16 v[32:35], v[244:247], v[182:185], v[32:35]
	v_mfma_f32_16x16x32_bf16 v[24:27], v[236:239], v[190:193], v[24:27]
	v_mfma_f32_16x16x32_bf16 v[16:19], v[244:247], v[190:193], v[16:19]
	v_mfma_f32_16x16x32_bf16 v[8:11], v[236:239], v[198:201], v[8:11]
	v_mfma_f32_16x16x32_bf16 v[0:3], v[244:247], v[198:201], v[0:3]
	s_setprio 0
	s_add_u32 s25, s25, 0x100
	s_addc_u32 s38, s38, 0
	s_add_u32 s30, s30, 0x100
	s_addc_u32 s31, s31, 0
	s_cmp_ge_i32 s39, s41
	s_mov_b32 s20, s39
	s_barrier
	s_cbranch_scc0 .LBB0_678
	v_readlane_b32 s20, v254, 5
	v_readlane_b32 s21, v254, 6
	s_mov_b64 s[82:83], 0xb00
	s_add_u32 s34, s20, 0xc400000
	s_addc_u32 s35, s21, 0
